# attention tile body hand-scheduled (all LDS fragment reads up front, max3 tree, in-place exp2 groups with early PV MFMAs) + XCD barrier at prologue seam
# speedup vs baseline: 1.0640x; 1.0165x over previous
; #define LAS __attribute__((address_space(3)))
; #define AT_LOAD(K_, V_, kt) do { const bf16_t* s_ = kvsrc + (size_t)(kt) * 64 * NQKV; K_ = *(const bf16x8*)s_; V_ = *(const bf16x8*)(s_ + 1024); } while (0)
; __device__ __forceinline__ void attn_tile(const LAS unsigned char* Kb, const LAS unsigned char* Vb, const LAS f32x4* bp, const bf16x8 (&qr)[4], f32x16 (&o)[2], float& m, float& l, int r32, int hi) {
;     const float C2 = 0.125f * LOG2E;
;     f32x16 p0, p1;
; #pragma unroll
;     for (int j = 0; j < 4; ++j) { const f32x4 t0 = bp[j * 64], t1 = bp[(4 + j) * 64];
;         p0[4 * j] = t0[0]; p0[4 * j + 1] = t0[1]; p0[4 * j + 2] = t0[2]; p0[4 * j + 3] = t0[3]; p1[4 * j] = t1[0]; p1[4 * j + 1] = t1[1]; p1[4 * j + 2] = t1[2]; p1[4 * j + 3] = t1[3]; }
; #pragma unroll
;     for (int d0 = 0; d0 < 4; ++d0) {
;         const bf16x8 a0 = *(const LAS bf16x8*)(Kb + r32 * 144 + d0 * 32 + hi * 16);
;         const bf16x8 a1 = *(const LAS bf16x8*)(Kb + (32 + r32) * 144 + d0 * 32 + hi * 16);
;         p0 = __builtin_amdgcn_mfma_f32_32x32x16_bf16(a0, qr[d0], p0, 0, 0, 0);
;         p1 = __builtin_amdgcn_mfma_f32_32x32x16_bf16(a1, qr[d0], p1, 0, 0, 0);
;     }
;     float mx = fmaxf(p0[0], p1[0]);
; #pragma unroll
;     for (int r = 1; r < 16; ++r) mx = fmaxf(mx, fmaxf(p0[r], p1[r]));
;     mx = fmaxf(mx, __shfl_xor(mx, 32)) * C2;
;     if (__any(mx > m + 8.0f)) {
;         const float mn = fmaxf(m, mx), scl = __builtin_amdgcn_exp2f(m - mn); m = mn; l *= scl;
; #pragma unroll
;         for (int r = 0; r < 16; ++r) { o[0][r] *= scl; o[1][r] *= scl; }
;     }
; __device__ __forceinline__ void attn_prompt_unit(const Params& P, LAS unsigned char* lds, int li, int b, int h, int g4, const int tid) {
;     ...
;     for (int kt = kt_lo; kt <= kt_hi; kt += 2) {
;         if (kt + 2 <= kt_hi) AT_LOAD(kA, vA, kt + 2);
;         if (kt >= cw - 8 && kt <= cw) attn_tile(lds + AT_KOFF, lds + AT_VOFF, btl + min(cw - kt, 3) * 1024, qr, o, m, l, r32, hi);
.LBB0_73:
	s_cmp_lt_i32 s28, s25
	s_cselect_b64 s[30:31], -1, 0
	s_cmp_gt_i32 s28, s23
	s_cselect_b64 s[34:35], -1, 0
	s_or_b64 s[30:31], s[30:31], s[34:35]
	s_and_b64 vcc, exec, s[30:31]
	s_cbranch_vccnz .LBB0_77
	s_add_i32 s29, s22, s26
	s_add_i32 s29, s29, 1
	s_min_i32 s29, s29, 3
	v_lshl_add_u32 v158, s29, 14, v103
	ds_read_b128 v[48:51], v158 offset:36864
	ds_read_b128 v[52:55], v158 offset:37888
	ds_read_b128 v[56:59], v158 offset:38912
	ds_read_b128 v[60:63], v158 offset:39936
	ds_read_b128 v[138:141], v116 offset:0
	ds_read_b128 v[142:145], v116 offset:4608
	ds_read_b128 v[32:35], v158 offset:40960
	ds_read_b128 v[36:39], v158 offset:41984
	ds_read_b128 v[40:43], v158 offset:43008
	ds_read_b128 v[44:47], v158 offset:44032
	ds_read_b128 v[146:149], v116 offset:32
	ds_read_b128 v[150:153], v116 offset:4640
	ds_read_b128 v[154:157], v116 offset:64
	ds_read_b128 v[118:121], v116 offset:4672
	ds_read_b128 v[122:125], v116 offset:96
	v_add_u32_e32 v133, v113, v112
	v_xor_b32_e32 v132, 32, v200
	s_waitcnt vmcnt(2) lgkmcnt(10)
	v_mfma_f32_32x32x16_bf16 v[48:63], v[138:141], v[64:67], v[48:63]
	ds_read_b128 v[126:129], v116 offset:4704
	s_waitcnt lgkmcnt(6)
	v_mfma_f32_32x32x16_bf16 v[32:47], v[142:145], v[64:67], v[32:47]
	v_lshlrev_b32_e32 v132, 2, v132
	s_waitcnt lgkmcnt(5)
	v_mfma_f32_32x32x16_bf16 v[48:63], v[146:149], v[68:71], v[48:63]
	s_waitcnt lgkmcnt(4)
	v_mfma_f32_32x32x16_bf16 v[32:47], v[150:153], v[68:71], v[32:47]
	s_waitcnt lgkmcnt(3)
	v_mfma_f32_32x32x16_bf16 v[48:63], v[154:157], v[72:75], v[48:63]
	s_waitcnt lgkmcnt(2)
	v_mfma_f32_32x32x16_bf16 v[32:47], v[118:121], v[72:75], v[32:47]
	s_waitcnt lgkmcnt(1)
	v_mfma_f32_32x32x16_bf16 v[48:63], v[122:125], v[80:83], v[48:63]
	s_waitcnt lgkmcnt(0)
	v_mfma_f32_32x32x16_bf16 v[32:47], v[126:129], v[80:83], v[32:47]
	ds_read_b128 v[138:141], v133 offset:18432
	ds_read_b128 v[142:145], v133 offset:18464
	ds_read_b128 v[146:149], v133 offset:18496
	ds_read_b128 v[150:153], v133 offset:18528
	ds_read_b128 v[154:157], v133 offset:23040
	ds_read_b128 v[118:121], v133 offset:23072
	ds_read_b128 v[122:125], v133 offset:23104
	ds_read_b128 v[126:129], v133 offset:23136
	v_add_f32_e32 v159, 0x41000000, v117
	s_nop 1
	v_max3_f32 v130, v48, v49, v50
	v_max3_f32 v130, v130, v51, v52
	v_max3_f32 v130, v130, v53, v54
	v_max3_f32 v131, v32, v33, v34
	v_max3_f32 v130, v130, v55, v56
	v_max3_f32 v131, v131, v35, v36
	v_max3_f32 v130, v130, v57, v58
	v_max3_f32 v131, v131, v37, v38
	v_max3_f32 v130, v130, v59, v60
	v_max3_f32 v131, v131, v39, v40
	v_max3_f32 v130, v130, v61, v62
	v_max3_f32 v131, v131, v41, v42
	v_max_f32_e32 v130, v130, v63
	v_max3_f32 v131, v131, v43, v44
	v_max3_f32 v131, v131, v45, v46
	v_max_f32_e32 v131, v131, v47
	v_max_f32_e32 v130, v130, v131
	ds_bpermute_b32 v131, v132, v130
	s_waitcnt lgkmcnt(0)
	v_max_f32_e32 v130, v130, v131
	v_mul_f32_e32 v130, 0x3e38aa3b, v130
	v_cmp_gt_f32_e32 vcc, v130, v159
	s_cbranch_vccz .Latt_keep_a
	v_max_f32_e32 v131, v117, v130
	v_sub_f32_e32 v117, v117, v131
	v_exp_f32_e32 v130, v117
	v_mov_b32_e32 v117, v131
	v_mul_f32_e32 v101, v101, v130
	v_pk_mul_f32 v[0:1], v[0:1], v[130:131] op_sel_hi:[1,0]
	v_pk_mul_f32 v[2:3], v[2:3], v[130:131] op_sel_hi:[1,0]
	v_pk_mul_f32 v[4:5], v[4:5], v[130:131] op_sel_hi:[1,0]
	v_pk_mul_f32 v[6:7], v[6:7], v[130:131] op_sel_hi:[1,0]
	v_pk_mul_f32 v[8:9], v[8:9], v[130:131] op_sel_hi:[1,0]
	v_pk_mul_f32 v[10:11], v[10:11], v[130:131] op_sel_hi:[1,0]
	v_pk_mul_f32 v[12:13], v[12:13], v[130:131] op_sel_hi:[1,0]
	v_pk_mul_f32 v[14:15], v[14:15], v[130:131] op_sel_hi:[1,0]
	v_pk_mul_f32 v[16:17], v[16:17], v[130:131] op_sel_hi:[1,0]
	v_pk_mul_f32 v[18:19], v[18:19], v[130:131] op_sel_hi:[1,0]
	v_pk_mul_f32 v[20:21], v[20:21], v[130:131] op_sel_hi:[1,0]
	v_pk_mul_f32 v[22:23], v[22:23], v[130:131] op_sel_hi:[1,0]
	v_pk_mul_f32 v[24:25], v[24:25], v[130:131] op_sel_hi:[1,0]
	v_pk_mul_f32 v[26:27], v[26:27], v[130:131] op_sel_hi:[1,0]
	v_pk_mul_f32 v[28:29], v[28:29], v[130:131] op_sel_hi:[1,0]
	v_pk_mul_f32 v[30:31], v[30:31], v[130:131] op_sel_hi:[1,0]
; #define LAS __attribute__((address_space(3)))
; __device__ __forceinline__ unsigned pk2(float lo, float hi) { const f32x2 v = {lo, hi}; return __builtin_bit_cast(unsigned, __builtin_convertvector(v, hwbf16x2)); }
; __device__ __forceinline__ void attn_tile(const LAS unsigned char* Kb, const LAS unsigned char* Vb, const LAS f32x4* bp, const bf16x8 (&qr)[4], f32x16 (&o)[2], float& m, float& l, int r32, int hi) {
;     ...
;     float ls = 0.f; const float nm = -m;
; #pragma unroll
;     for (int r = 0; r < 16; ++r) { p0[r] = __builtin_amdgcn_exp2f(p0[r] * C2 + nm); p1[r] = __builtin_amdgcn_exp2f(p1[r] * C2 + nm); ls += p0[r] + p1[r]; }
;     l += ls;
;     u32x4 pw[4];
; #pragma unroll
;     for (int s = 0; s < 2; ++s) {
;         pw[s] = (u32x4){pk2(p0[8 * s], p0[8 * s + 1]), pk2(p0[8 * s + 2], p0[8 * s + 3]), pk2(p0[8 * s + 4], p0[8 * s + 5]), pk2(p0[8 * s + 6], p0[8 * s + 7])};
;         pw[2 + s] = (u32x4){pk2(p1[8 * s], p1[8 * s + 1]), pk2(p1[8 * s + 2], p1[8 * s + 3]), pk2(p1[8 * s + 4], p1[8 * s + 5]), pk2(p1[8 * s + 6], p1[8 * s + 7])};
;     }
; #pragma unroll
;     for (int dh = 0; dh < 2; ++dh)
; #pragma unroll
;         for (int ks = 0; ks < 4; ++ks) {
;             const bf16x8 vf = *(const LAS bf16x8*)(Vb + (32 * dh + r32) * 144 + (16 * ks + 8 * hi) * 2);
;             o[dh] = __builtin_amdgcn_mfma_f32_32x32x16_bf16(vf, __builtin_bit_cast(bf16x8, pw[ks]), o[dh], 0, 0, 0);
;         }
.Latt_keep_a:
	v_fma_f32 v48, v48, s6, -v117
	v_fma_f32 v49, v49, s6, -v117
	v_fma_f32 v50, v50, s6, -v117
	v_fma_f32 v51, v51, s6, -v117
	v_fma_f32 v52, v52, s6, -v117
	v_fma_f32 v53, v53, s6, -v117
	v_fma_f32 v54, v54, s6, -v117
	v_fma_f32 v55, v55, s6, -v117
	v_exp_f32_e32 v48, v48
	v_exp_f32_e32 v49, v49
	v_exp_f32_e32 v50, v50
	v_exp_f32_e32 v51, v51
	v_exp_f32_e32 v52, v52
	v_exp_f32_e32 v53, v53
	v_exp_f32_e32 v54, v54
	v_exp_f32_e32 v55, v55
	v_add_f32_e32 v130, v48, v49
	v_add_f32_e32 v131, v50, v51
	v_add_f32_e32 v130, v130, v52
	v_add_f32_e32 v131, v131, v53
	v_add_f32_e32 v130, v130, v54
	v_add_f32_e32 v131, v131, v55
	v_cvt_pk_bf16_f32 v48, v48, v49
	v_cvt_pk_bf16_f32 v49, v50, v51
	v_cvt_pk_bf16_f32 v50, v52, v53
	v_cvt_pk_bf16_f32 v51, v54, v55
	v_fma_f32 v56, v56, s6, -v117
	v_fma_f32 v57, v57, s6, -v117
	v_fma_f32 v58, v58, s6, -v117
	v_fma_f32 v59, v59, s6, -v117
	v_fma_f32 v60, v60, s6, -v117
	v_fma_f32 v61, v61, s6, -v117
	v_fma_f32 v62, v62, s6, -v117
	v_fma_f32 v63, v63, s6, -v117
	v_exp_f32_e32 v56, v56
	v_exp_f32_e32 v57, v57
	v_exp_f32_e32 v58, v58
	v_exp_f32_e32 v59, v59
	v_exp_f32_e32 v60, v60
	v_exp_f32_e32 v61, v61
	v_exp_f32_e32 v62, v62
	v_exp_f32_e32 v63, v63
	v_mfma_f32_32x32x16_bf16 v[16:31], v[138:141], v[48:51], v[16:31]
	v_mfma_f32_32x32x16_bf16 v[0:15], v[154:157], v[48:51], v[0:15]
	v_add_f32_e32 v130, v130, v56
	v_add_f32_e32 v131, v131, v57
	v_add_f32_e32 v130, v130, v58
	v_add_f32_e32 v131, v131, v59
	v_add_f32_e32 v130, v130, v60
	v_add_f32_e32 v131, v131, v61
	v_add_f32_e32 v130, v130, v62
	v_add_f32_e32 v131, v131, v63
	v_cvt_pk_bf16_f32 v52, v56, v57
	v_cvt_pk_bf16_f32 v53, v58, v59
	v_cvt_pk_bf16_f32 v54, v60, v61
	v_cvt_pk_bf16_f32 v55, v62, v63
	v_fma_f32 v32, v32, s6, -v117
	v_fma_f32 v33, v33, s6, -v117
	v_fma_f32 v34, v34, s6, -v117
	v_fma_f32 v35, v35, s6, -v117
	v_fma_f32 v36, v36, s6, -v117
	v_fma_f32 v37, v37, s6, -v117
	v_fma_f32 v38, v38, s6, -v117
	v_fma_f32 v39, v39, s6, -v117
	v_exp_f32_e32 v32, v32
	v_exp_f32_e32 v33, v33
	v_exp_f32_e32 v34, v34
	v_exp_f32_e32 v35, v35
	v_exp_f32_e32 v36, v36
	v_exp_f32_e32 v37, v37
	v_exp_f32_e32 v38, v38
	v_exp_f32_e32 v39, v39
	v_mfma_f32_32x32x16_bf16 v[16:31], v[142:145], v[52:55], v[16:31]
	v_mfma_f32_32x32x16_bf16 v[0:15], v[118:121], v[52:55], v[0:15]
	v_add_f32_e32 v130, v130, v32
	v_add_f32_e32 v131, v131, v33
	v_add_f32_e32 v130, v130, v34
	v_add_f32_e32 v131, v131, v35
	v_add_f32_e32 v130, v130, v36
	v_add_f32_e32 v131, v131, v37
	v_add_f32_e32 v130, v130, v38
	v_add_f32_e32 v131, v131, v39
	v_cvt_pk_bf16_f32 v32, v32, v33
	v_cvt_pk_bf16_f32 v33, v34, v35
	v_cvt_pk_bf16_f32 v34, v36, v37
	v_cvt_pk_bf16_f32 v35, v38, v39
	v_fma_f32 v40, v40, s6, -v117
	v_fma_f32 v41, v41, s6, -v117
	v_fma_f32 v42, v42, s6, -v117
	v_fma_f32 v43, v43, s6, -v117
	v_fma_f32 v44, v44, s6, -v117
	v_fma_f32 v45, v45, s6, -v117
	v_fma_f32 v46, v46, s6, -v117
	v_fma_f32 v47, v47, s6, -v117
	v_exp_f32_e32 v40, v40
	v_exp_f32_e32 v41, v41
	v_exp_f32_e32 v42, v42
	v_exp_f32_e32 v43, v43
	v_exp_f32_e32 v44, v44
	v_exp_f32_e32 v45, v45
	v_exp_f32_e32 v46, v46
	v_exp_f32_e32 v47, v47
	v_mfma_f32_32x32x16_bf16 v[16:31], v[146:149], v[32:35], v[16:31]
	v_mfma_f32_32x32x16_bf16 v[0:15], v[122:125], v[32:35], v[0:15]
	v_add_f32_e32 v130, v130, v40
	v_add_f32_e32 v131, v131, v41
	v_add_f32_e32 v130, v130, v42
	v_add_f32_e32 v131, v131, v43
	v_add_f32_e32 v130, v130, v44
	v_add_f32_e32 v131, v131, v45
	v_add_f32_e32 v130, v130, v46
	v_add_f32_e32 v131, v131, v47
	v_cvt_pk_bf16_f32 v36, v40, v41
	v_cvt_pk_bf16_f32 v37, v42, v43
	v_cvt_pk_bf16_f32 v38, v44, v45
	v_cvt_pk_bf16_f32 v39, v46, v47
	v_add_f32_e32 v130, v130, v131
	v_add_f32_e32 v101, v101, v130
	v_mfma_f32_32x32x16_bf16 v[16:31], v[150:153], v[36:39], v[16:31]
	v_mfma_f32_32x32x16_bf16 v[0:15], v[126:129], v[36:39], v[0:15]

; #define LAS __attribute__((address_space(3)))
; #define AT_LOAD(K_, V_, kt) do { const bf16_t* s_ = kvsrc + (size_t)(kt) * 64 * NQKV; K_ = *(const bf16x8*)s_; V_ = *(const bf16x8*)(s_ + 1024); } while (0)
; __device__ __forceinline__ void attn_tile(const LAS unsigned char* Kb, const LAS unsigned char* Vb, const LAS f32x4* bp, const bf16x8 (&qr)[4], f32x16 (&o)[2], float& m, float& l, int r32, int hi) {
;     const float C2 = 0.125f * LOG2E;
;     f32x16 p0, p1;
; #pragma unroll
;     for (int j = 0; j < 4; ++j) { const f32x4 t0 = bp[j * 64], t1 = bp[(4 + j) * 64];
;         p0[4 * j] = t0[0]; p0[4 * j + 1] = t0[1]; p0[4 * j + 2] = t0[2]; p0[4 * j + 3] = t0[3]; p1[4 * j] = t1[0]; p1[4 * j + 1] = t1[1]; p1[4 * j + 2] = t1[2]; p1[4 * j + 3] = t1[3]; }
; #pragma unroll
;     for (int d0 = 0; d0 < 4; ++d0) {
;         const bf16x8 a0 = *(const LAS bf16x8*)(Kb + r32 * 144 + d0 * 32 + hi * 16);
;         const bf16x8 a1 = *(const LAS bf16x8*)(Kb + (32 + r32) * 144 + d0 * 32 + hi * 16);
;         p0 = __builtin_amdgcn_mfma_f32_32x32x16_bf16(a0, qr[d0], p0, 0, 0, 0);
;         p1 = __builtin_amdgcn_mfma_f32_32x32x16_bf16(a1, qr[d0], p1, 0, 0, 0);
;     }
;     float mx = fmaxf(p0[0], p1[0]);
; #pragma unroll
;     for (int r = 1; r < 16; ++r) mx = fmaxf(mx, fmaxf(p0[r], p1[r]));
;     mx = fmaxf(mx, __shfl_xor(mx, 32)) * C2;
;     if (__any(mx > m + 8.0f)) {
;         const float mn = fmaxf(m, mx), scl = __builtin_amdgcn_exp2f(m - mn); m = mn; l *= scl;
; #pragma unroll
;         for (int r = 0; r < 16; ++r) { o[0][r] *= scl; o[1][r] *= scl; }
;     }
; __device__ __forceinline__ void attn_prompt_unit(const Params& P, LAS unsigned char* lds, int li, int b, int h, int g4, const int tid) {
;     ...
;         if (kt + 3 <= kt_hi) AT_LOAD(kB, vB, kt + 3);
;         if (kt + 1 >= cw - 8 && kt + 1 <= cw) attn_tile(lds + AT_KOFF + 9216, lds + AT_VOFF + 9216, btl + min(cw - kt - 1, 3) * 1024, qr, o, m, l, r32, hi);
.LBB0_79:
	s_add_i32 s29, s28, 1
	s_cmp_lt_i32 s29, s25
	s_cselect_b64 s[30:31], -1, 0
	s_cmp_ge_i32 s28, s23
	s_cselect_b64 s[28:29], -1, 0
	s_or_b64 s[28:29], s[28:29], s[30:31]
	s_and_b64 vcc, exec, s[28:29]
	s_cbranch_vccnz .LBB0_83
	s_add_i32 s28, s22, s26
	s_min_i32 s28, s28, 3
	v_lshl_add_u32 v158, s28, 14, v103
	ds_read_b128 v[48:51], v158 offset:36864
	ds_read_b128 v[52:55], v158 offset:37888
	ds_read_b128 v[56:59], v158 offset:38912
	ds_read_b128 v[60:63], v158 offset:39936
	ds_read_b128 v[138:141], v116 offset:9216
	ds_read_b128 v[142:145], v116 offset:13824
	ds_read_b128 v[32:35], v158 offset:40960
	ds_read_b128 v[36:39], v158 offset:41984
	ds_read_b128 v[40:43], v158 offset:43008
	ds_read_b128 v[44:47], v158 offset:44032
	ds_read_b128 v[146:149], v116 offset:9248
	ds_read_b128 v[150:153], v116 offset:13856
	ds_read_b128 v[154:157], v116 offset:9280
	ds_read_b128 v[118:121], v116 offset:13888
	ds_read_b128 v[122:125], v116 offset:9312
	v_add_u32_e32 v133, v113, v112
	v_xor_b32_e32 v132, 32, v200
	s_waitcnt lgkmcnt(10)
	v_mfma_f32_32x32x16_bf16 v[48:63], v[138:141], v[64:67], v[48:63]
	ds_read_b128 v[126:129], v116 offset:13920
	s_waitcnt lgkmcnt(6)
	v_mfma_f32_32x32x16_bf16 v[32:47], v[142:145], v[64:67], v[32:47]
	v_lshlrev_b32_e32 v132, 2, v132
	s_waitcnt lgkmcnt(5)
	v_mfma_f32_32x32x16_bf16 v[48:63], v[146:149], v[68:71], v[48:63]
	s_waitcnt lgkmcnt(4)
	v_mfma_f32_32x32x16_bf16 v[32:47], v[150:153], v[68:71], v[32:47]
	s_waitcnt lgkmcnt(3)
	v_mfma_f32_32x32x16_bf16 v[48:63], v[154:157], v[72:75], v[48:63]
	s_waitcnt lgkmcnt(2)
	v_mfma_f32_32x32x16_bf16 v[32:47], v[118:121], v[72:75], v[32:47]
	s_waitcnt lgkmcnt(1)
	v_mfma_f32_32x32x16_bf16 v[48:63], v[122:125], v[80:83], v[48:63]
	s_waitcnt lgkmcnt(0)
	v_mfma_f32_32x32x16_bf16 v[32:47], v[126:129], v[80:83], v[32:47]
	ds_read_b128 v[138:141], v133 offset:27648
	ds_read_b128 v[142:145], v133 offset:27680
	ds_read_b128 v[146:149], v133 offset:27712
	ds_read_b128 v[150:153], v133 offset:27744
	ds_read_b128 v[154:157], v133 offset:32256
	ds_read_b128 v[118:121], v133 offset:32288
	ds_read_b128 v[122:125], v133 offset:32320
	ds_read_b128 v[126:129], v133 offset:32352
	v_add_f32_e32 v159, 0x41000000, v117
	s_nop 1
	v_max3_f32 v130, v48, v49, v50
	v_max3_f32 v130, v130, v51, v52
	v_max3_f32 v130, v130, v53, v54
	v_max3_f32 v131, v32, v33, v34
	v_max3_f32 v130, v130, v55, v56
	v_max3_f32 v131, v131, v35, v36
	v_max3_f32 v130, v130, v57, v58
	v_max3_f32 v131, v131, v37, v38
	v_max3_f32 v130, v130, v59, v60
	v_max3_f32 v131, v131, v39, v40
	v_max3_f32 v130, v130, v61, v62
	v_max3_f32 v131, v131, v41, v42
	v_max_f32_e32 v130, v130, v63
	v_max3_f32 v131, v131, v43, v44
	v_max3_f32 v131, v131, v45, v46
	v_max_f32_e32 v131, v131, v47
	v_max_f32_e32 v130, v130, v131
	ds_bpermute_b32 v131, v132, v130
	s_waitcnt lgkmcnt(0)
	v_max_f32_e32 v130, v130, v131
	v_mul_f32_e32 v130, 0x3e38aa3b, v130
	v_cmp_gt_f32_e32 vcc, v130, v159
	s_cbranch_vccz .Latt_keep_b
	v_max_f32_e32 v131, v117, v130
	v_sub_f32_e32 v117, v117, v131
	v_exp_f32_e32 v130, v117
	v_mov_b32_e32 v117, v131
	v_mul_f32_e32 v101, v101, v130
	v_pk_mul_f32 v[0:1], v[0:1], v[130:131] op_sel_hi:[1,0]
	v_pk_mul_f32 v[2:3], v[2:3], v[130:131] op_sel_hi:[1,0]
	v_pk_mul_f32 v[4:5], v[4:5], v[130:131] op_sel_hi:[1,0]
	v_pk_mul_f32 v[6:7], v[6:7], v[130:131] op_sel_hi:[1,0]
	v_pk_mul_f32 v[8:9], v[8:9], v[130:131] op_sel_hi:[1,0]
	v_pk_mul_f32 v[10:11], v[10:11], v[130:131] op_sel_hi:[1,0]
	v_pk_mul_f32 v[12:13], v[12:13], v[130:131] op_sel_hi:[1,0]
	v_pk_mul_f32 v[14:15], v[14:15], v[130:131] op_sel_hi:[1,0]
	v_pk_mul_f32 v[16:17], v[16:17], v[130:131] op_sel_hi:[1,0]
	v_pk_mul_f32 v[18:19], v[18:19], v[130:131] op_sel_hi:[1,0]
	v_pk_mul_f32 v[20:21], v[20:21], v[130:131] op_sel_hi:[1,0]
	v_pk_mul_f32 v[22:23], v[22:23], v[130:131] op_sel_hi:[1,0]
	v_pk_mul_f32 v[24:25], v[24:25], v[130:131] op_sel_hi:[1,0]
	v_pk_mul_f32 v[26:27], v[26:27], v[130:131] op_sel_hi:[1,0]
	v_pk_mul_f32 v[28:29], v[28:29], v[130:131] op_sel_hi:[1,0]
	v_pk_mul_f32 v[30:31], v[30:31], v[130:131] op_sel_hi:[1,0]

; __device__ __forceinline__ void xcd_barrier(const XcdBarrier& b) {
;     asm volatile("s_waitcnt vmcnt(0)" ::: "memory");
;     __syncthreads();
;     if (threadIdx.x == 0) {
;         unsigned* bar = b.bar;
;         __builtin_amdgcn_s_waitcnt(0);
;         unsigned nloc = b.st[0], nx = b.st[1];
;         if (nloc == 0u) { xcd_barrier_complete(bar, b.x, nloc, nx); b.st[0] = nloc; b.st[1] = nx; }
; __global__ void __launch_bounds__(512, 2) hybrid_fwd(Params P) {
;     ...
;         if (++rep >= nrep) { rep = 0; ++ph; }
;         if (ph < P.ph_hi) { if (ph == 1 && rep == 0) cg::this_grid().sync(); else xcd_barrier(xbar); }
.LBB0_566:
	s_add_i32 s94, s68, 1
	s_cmp_ge_i32 s94, s95
	s_mov_b64 s[0:1], -1
	s_mov_b64 s[10:11], s[86:87]
	s_cbranch_scc1 .LBB0_10
	s_waitcnt vmcnt(0)
	s_waitcnt lgkmcnt(0)
	s_barrier
	s_mov_b64 s[0:1], exec
	v_readlane_b32 s10, v247, 3
	v_readlane_b32 s11, v247, 4
	s_and_b64 s[10:11], s[0:1], s[10:11]
	s_mov_b64 exec, s[10:11]
	s_cbranch_execz .LBB0_620
	v_readlane_b32 s2, v245, 12
	s_waitcnt vmcnt(0) expcnt(0) lgkmcnt(0)
	s_nop 0
	v_mov_b32_e32 v0, s2
	ds_read_b32 v2, v0
	v_readlane_b32 s2, v245, 13
	s_waitcnt lgkmcnt(0)
	v_cmp_ne_u32_e32 vcc, 0, v2
	v_mov_b32_e32 v0, s2
	ds_read_b32 v0, v0
	s_cbranch_vccnz .LBB0_584
	v_readlane_b32 s12, v247, 1
	v_readlane_b32 s13, v247, 2
	s_load_dwordx2 s[10:11], s[12:13], 0x4
	s_mov_b32 s4, 1
	s_waitcnt lgkmcnt(0)
	s_mul_i32 s2, s10, s33
	s_mul_i32 s2, s2, s11
	s_branch .LBB0_572
